# gate/up GEMM: first K-iteration peeled, accumulators start from MFMA C=0 instead of 128 v_mov zero-init
# speedup vs baseline: 1.0090x; 1.0020x over previous
; #define PG8_STAGE(bufoff, gbase, voff) do { _Pragma("unroll") for (int _i = 0; _i < 2; ++_i) \
;         __builtin_amdgcn_global_load_lds((const unsigned*)((const char*)(gbase) + (voff)[_i]), (LAS unsigned*)(lds + (bufoff) + ldsw + _i * 8192), 16, 0, 0); } while (0)
; #define PG8_LDA(dst, b, h) do { _Pragma("unroll") for (int m = 0; m < 4; ++m) _Pragma("unroll") for (int k = 0; k < 2; ++k) dst[m][k] = *(const LAS bf16x8*)(lds + PG8_SA(b, h) + aoff + m * 2048 + k * 1024); } while (0)
; #define PG8_LDB(dst, b, h) do { _Pragma("unroll") for (int n = 0; n < 2; ++n) _Pragma("unroll") for (int k = 0; k < 2; ++k) dst[n][k] = *(const LAS bf16x8*)(lds + PG8_SB(b, h) + boff + n * 2048 + k * 1024); } while (0)
; #define PG8_MMA(ai, bj, At, Bt) do { __builtin_amdgcn_s_setprio(1); _Pragma("unroll") for (int m = 0; m < 4; ++m) _Pragma("unroll") for (int n = 0; n < 2; ++n) _Pragma("unroll") for (int k = 0; k < 2; ++k) \
;         acc[ai][bj][m][n] = __builtin_amdgcn_mfma_f32_16x16x32_bf16(Bt[n][k], At[m][k], acc[ai][bj][m][n], 0, 0, 0); __builtin_amdgcn_s_setprio(0); } while (0)
; #define PG8_BAR __builtin_amdgcn_s_barrier()
; template <class Epi, class Sched>
; __device__ __forceinline__ void gemm_phase(LAS unsigned char* lds, const Gemm g, const Sched& S, const Epi& E, const Ids I) {
;     ...
;         const bool has_next = S.next(ui + 1, nxt);
;         const char* nA = has_next ? (const char*)g.A + (size_t)nxt.pm * tstep + nxt.kb : cA; const char* nB = has_next ? (const char*)g.Bt + (size_t)nxt.pn * tstep + nxt.kb : cB;
;         for (int t = 0; t < nt; t += 2) {
;             const bool last = (t == nt - 2);
;             const char* a1 = cA + (size_t)(t + 1) * kstep;
;             const char* a2 = last ? nA : cA + (size_t)(t + 2) * kstep; const char* b2 = last ? nB : cB + (size_t)(t + 2) * kstep;
;             const char* a3 = a2 + kstep; const char* b3 = b2 + kstep;
;             PG8_LDB(B0, 0, 0); PG8_SCHED; PG8_LDA(At, 0, 0); PG8_STAGE(PG8_SA(1, 1), a1 + hstep, voffA);
;             PG8_WAIT_L(8); PG8_BAR; PG8_WAIT_L(0); PG8_MMA(0, 0, At, B0); PG8_BAR; PG8_SCHED;
;             PG8_LDB(B1, 0, 1); PG8_STAGE(PG8_SB(0, 0), b2, voffB);
;             PG8_BAR; PG8_WAIT_L(0); PG8_MMA(0, 1, At, B1); PG8_BAR;
;             PG8_LDA(At, 0, 1); PG8_STAGE(PG8_SA(0, 0), a2, voffA);
;             PG8_BAR; PG8_WAIT_L(0); PG8_MMA(1, 0, At, B0); PG8_BAR; PG8_SCHED;
.LBB0_407:
	v_mov_b64_e32 v[0:1], 0x5ac
	s_ashr_i32 s9, s8, 31
	v_cmp_lt_i64_e32 vcc, s[10:11], v[0:1]
	s_lshl_b64 s[10:11], s[8:9], 19
	s_add_u32 s10, s78, s10
	s_addc_u32 s11, s79, s11
	s_and_b64 s[14:15], vcc, exec
	s_cselect_b32 s3, s11, s19
	s_cselect_b32 s9, s10, s18
	s_ashr_i32 s7, s6, 31
	s_lshl_b64 s[14:15], s[6:7], 19
	s_add_u32 s14, s26, s14
	s_addc_u32 s15, s27, s15
	s_and_b64 s[22:23], vcc, exec
	s_cselect_b32 s7, s15, s21
	s_cselect_b32 s35, s14, s20
	s_add_u32 s18, s18, 0x40080
	s_addc_u32 s19, s19, 0
	s_add_u32 s36, s20, 0x100
	s_addc_u32 s37, s21, 0
	s_mov_b32 s38, -2
	s_add_u32 s20, s18, 0xfffc0080
	s_addc_u32 s21, s19, -1
	s_add_i32 s39, 0, 0x10000
	v_add_u32_e32 v134, s39, v137
	ds_read_b128 v[140:143], v134
	ds_read_b128 v[152:155], v134 offset:1024
	ds_read_b128 v[156:159], v134 offset:2048
	ds_read_b128 v[160:163], v134 offset:3072
	s_cmp_eq_u32 s38, 12
	s_cselect_b32 s23, s3, s21
	s_cselect_b32 s22, s9, s20
	s_cselect_b32 s21, s7, s37
	s_cselect_b32 s20, s35, s36
	v_lshl_add_u64 v[134:135], s[18:19], 0, v[130:131]
	s_add_i32 m0, s17, 0xc000
	ds_read_b128 v[164:167], v139
	ds_read_b128 v[168:171], v139 offset:1024
	ds_read_b128 v[188:191], v139 offset:2048
	ds_read_b128 v[192:195], v139 offset:3072
	ds_read_b128 v[196:199], v139 offset:4096
	ds_read_b128 v[200:203], v139 offset:5120
	ds_read_b128 v[204:207], v139 offset:6144
	ds_read_b128 v[208:211], v139 offset:7168
	global_load_lds_dwordx4 v[134:135], off
	v_lshl_add_u64 v[134:135], s[18:19], 0, v[132:133]
	s_add_i32 m0, s17, 0xe000
	s_nop 0
	global_load_lds_dwordx4 v[134:135], off
	s_waitcnt lgkmcnt(8)
	s_barrier
	s_waitcnt lgkmcnt(0)
	s_setprio 1
	s_waitcnt lgkmcnt(0)
	v_mfma_f32_16x16x32_bf16 v[124:127], v[140:143], v[164:167], 0
	v_mfma_f32_16x16x32_bf16 v[116:119], v[156:159], v[164:167], 0
	v_mfma_f32_16x16x32_bf16 v[108:111], v[140:143], v[188:191], 0
	v_mfma_f32_16x16x32_bf16 v[100:103], v[156:159], v[188:191], 0
	v_mfma_f32_16x16x32_bf16 v[92:95], v[140:143], v[196:199], 0
	v_mfma_f32_16x16x32_bf16 v[84:87], v[156:159], v[196:199], 0
	v_mfma_f32_16x16x32_bf16 v[76:79], v[140:143], v[204:207], 0
	v_mfma_f32_16x16x32_bf16 v[68:71], v[156:159], v[204:207], 0
	v_mfma_f32_16x16x32_bf16 v[124:127], v[152:155], v[168:171], v[124:127]
	v_mfma_f32_16x16x32_bf16 v[116:119], v[160:163], v[168:171], v[116:119]
	v_mfma_f32_16x16x32_bf16 v[108:111], v[152:155], v[192:195], v[108:111]
	v_mfma_f32_16x16x32_bf16 v[100:103], v[160:163], v[192:195], v[100:103]
	v_mfma_f32_16x16x32_bf16 v[92:95], v[152:155], v[200:203], v[92:95]
	v_mfma_f32_16x16x32_bf16 v[84:87], v[160:163], v[200:203], v[84:87]
	v_mfma_f32_16x16x32_bf16 v[76:79], v[152:155], v[208:211], v[76:79]
	v_mfma_f32_16x16x32_bf16 v[68:71], v[160:163], v[208:211], v[68:71]
	s_setprio 0
	s_barrier
	s_add_i32 s42, 0, 0x14000
	v_add_u32_e32 v134, s42, v137
	s_add_i32 s39, s39, s25
	ds_read_b128 v[212:215], v134
	ds_read_b128 v[216:219], v134 offset:1024
	ds_read_b128 v[220:223], v134 offset:2048
	ds_read_b128 v[224:227], v134 offset:3072
	v_lshl_add_u64 v[134:135], s[20:21], 0, v[144:145]
	s_mov_b32 m0, s39
	v_lshl_add_u64 v[172:173], s[20:21], 0, v[128:129]
	global_load_lds_dwordx4 v[134:135], off
	s_add_i32 m0, s39, 0x2000
	s_nop 0
	global_load_lds_dwordx4 v[172:173], off
	s_barrier
	s_waitcnt lgkmcnt(0)
	s_setprio 1
	s_waitcnt lgkmcnt(0)
	v_mfma_f32_16x16x32_bf16 v[120:123], v[212:215], v[164:167], 0
	v_mfma_f32_16x16x32_bf16 v[112:115], v[220:223], v[164:167], 0
	v_mfma_f32_16x16x32_bf16 v[104:107], v[212:215], v[188:191], 0
	v_mfma_f32_16x16x32_bf16 v[96:99], v[220:223], v[188:191], 0
	v_mfma_f32_16x16x32_bf16 v[88:91], v[212:215], v[196:199], 0
	v_mfma_f32_16x16x32_bf16 v[80:83], v[220:223], v[196:199], 0
	v_mfma_f32_16x16x32_bf16 v[72:75], v[212:215], v[204:207], 0
	v_mfma_f32_16x16x32_bf16 v[64:67], v[220:223], v[204:207], 0
	v_mfma_f32_16x16x32_bf16 v[120:123], v[216:219], v[168:171], v[120:123]
	v_mfma_f32_16x16x32_bf16 v[112:115], v[224:227], v[168:171], v[112:115]
	v_mfma_f32_16x16x32_bf16 v[104:107], v[216:219], v[192:195], v[104:107]
	v_mfma_f32_16x16x32_bf16 v[96:99], v[224:227], v[192:195], v[96:99]
	v_mfma_f32_16x16x32_bf16 v[88:91], v[216:219], v[200:203], v[88:91]
	v_mfma_f32_16x16x32_bf16 v[80:83], v[224:227], v[200:203], v[80:83]
	v_mfma_f32_16x16x32_bf16 v[72:75], v[216:219], v[208:211], v[72:75]
	v_mfma_f32_16x16x32_bf16 v[64:67], v[224:227], v[208:211], v[64:67]
	s_setprio 0
	s_mov_b32 m0, s17
	v_lshl_add_u64 v[176:177], s[22:23], 0, v[144:145]
	s_barrier
	ds_read_b128 v[164:167], v139 offset:16384
	ds_read_b128 v[168:171], v139 offset:17408
	ds_read_b128 v[188:191], v139 offset:18432
	ds_read_b128 v[192:195], v139 offset:19456
	ds_read_b128 v[196:199], v139 offset:20480
	ds_read_b128 v[200:203], v139 offset:21504
	ds_read_b128 v[204:207], v139 offset:22528
	ds_read_b128 v[208:211], v139 offset:23552
	global_load_lds_dwordx4 v[176:177], off
	v_lshl_add_u64 v[178:179], s[22:23], 0, v[128:129]
	s_mov_b32 m0, s28
	s_nop 0
	global_load_lds_dwordx4 v[178:179], off
	s_barrier
	s_waitcnt lgkmcnt(0)
	s_setprio 1
	s_waitcnt lgkmcnt(0)
	v_mfma_f32_16x16x32_bf16 v[60:63], v[140:143], v[164:167], 0
	v_mfma_f32_16x16x32_bf16 v[52:55], v[156:159], v[164:167], 0
	v_mfma_f32_16x16x32_bf16 v[44:47], v[140:143], v[188:191], 0
	v_mfma_f32_16x16x32_bf16 v[36:39], v[156:159], v[188:191], 0
	v_mfma_f32_16x16x32_bf16 v[28:31], v[140:143], v[196:199], 0
	v_mfma_f32_16x16x32_bf16 v[20:23], v[156:159], v[196:199], 0
	v_mfma_f32_16x16x32_bf16 v[12:15], v[140:143], v[204:207], 0
	v_mfma_f32_16x16x32_bf16 v[4:7], v[156:159], v[204:207], 0
	v_mfma_f32_16x16x32_bf16 v[60:63], v[152:155], v[168:171], v[60:63]
	v_mfma_f32_16x16x32_bf16 v[52:55], v[160:163], v[168:171], v[52:55]
	v_mfma_f32_16x16x32_bf16 v[44:47], v[152:155], v[192:195], v[44:47]
	v_mfma_f32_16x16x32_bf16 v[36:39], v[160:163], v[192:195], v[36:39]
	v_mfma_f32_16x16x32_bf16 v[28:31], v[152:155], v[200:203], v[28:31]
	v_mfma_f32_16x16x32_bf16 v[20:23], v[160:163], v[200:203], v[20:23]
	v_mfma_f32_16x16x32_bf16 v[12:15], v[152:155], v[208:211], v[12:15]
	v_mfma_f32_16x16x32_bf16 v[4:7], v[160:163], v[208:211], v[4:7]
	s_setprio 0
	s_barrier
; #define PG8_STAGE(bufoff, gbase, voff) do { _Pragma("unroll") for (int _i = 0; _i < 2; ++_i) \
;         __builtin_amdgcn_global_load_lds((const unsigned*)((const char*)(gbase) + (voff)[_i]), (LAS unsigned*)(lds + (bufoff) + ldsw + _i * 8192), 16, 0, 0); } while (0)
; #define PG8_LDA(dst, b, h) do { _Pragma("unroll") for (int m = 0; m < 4; ++m) _Pragma("unroll") for (int k = 0; k < 2; ++k) dst[m][k] = *(const LAS bf16x8*)(lds + PG8_SA(b, h) + aoff + m * 2048 + k * 1024); } while (0)
; #define PG8_LDB(dst, b, h) do { _Pragma("unroll") for (int n = 0; n < 2; ++n) _Pragma("unroll") for (int k = 0; k < 2; ++k) dst[n][k] = *(const LAS bf16x8*)(lds + PG8_SB(b, h) + boff + n * 2048 + k * 1024); } while (0)
; #define PG8_MMA(ai, bj, At, Bt) do { __builtin_amdgcn_s_setprio(1); _Pragma("unroll") for (int m = 0; m < 4; ++m) _Pragma("unroll") for (int n = 0; n < 2; ++n) _Pragma("unroll") for (int k = 0; k < 2; ++k) \
;         acc[ai][bj][m][n] = __builtin_amdgcn_mfma_f32_16x16x32_bf16(Bt[n][k], At[m][k], acc[ai][bj][m][n], 0, 0, 0); __builtin_amdgcn_s_setprio(0); } while (0)
; #define PG8_WAIT_V(n) asm volatile("s_waitcnt vmcnt(" #n ")" ::: "memory")
; #define PG8_WAIT_L(n) asm volatile("s_waitcnt lgkmcnt(" #n ")" ::: "memory")
; #define PG8_BAR __builtin_amdgcn_s_barrier()
; #define PG8_SCHED __builtin_amdgcn_sched_barrier(0)
; template <class Epi, class Sched>
; __device__ __forceinline__ void gemm_phase(LAS unsigned char* lds, const Gemm g, const Sched& S, const Epi& E, const Ids I) {
;     ...
;             PG8_STAGE(PG8_SB(0, 1), b2 + hstep, voffB);
;             PG8_WAIT_V(6); PG8_BAR; PG8_MMA(1, 1, At, B1); PG8_BAR;
;             PG8_LDB(B0, 1, 0); PG8_SCHED; PG8_LDA(At, 1, 0); PG8_STAGE(PG8_SA(0, 1), a2 + hstep, voffA);
;             PG8_WAIT_L(8); PG8_BAR; PG8_WAIT_L(0); PG8_MMA(0, 0, At, B0); PG8_BAR; PG8_SCHED;
	s_add_u32 s40, s20, 0x40000
	s_addc_u32 s41, s21, 0
	s_add_i32 s39, s42, s25
	v_lshl_add_u64 v[140:141], s[40:41], 0, v[144:145]
	s_mov_b32 m0, s39
	s_nop 0
	global_load_lds_dwordx4 v[140:141], off
	v_lshl_add_u64 v[140:141], s[40:41], 0, v[128:129]
	s_add_i32 m0, s39, 0x2000
	s_nop 0
	global_load_lds_dwordx4 v[140:141], off
	s_waitcnt vmcnt(6)
	s_barrier
	s_setprio 1
	v_mfma_f32_16x16x32_bf16 v[56:59], v[212:215], v[164:167], 0
	v_mfma_f32_16x16x32_bf16 v[48:51], v[220:223], v[164:167], 0
	v_mfma_f32_16x16x32_bf16 v[40:43], v[212:215], v[188:191], 0
	v_mfma_f32_16x16x32_bf16 v[32:35], v[220:223], v[188:191], 0
	v_mfma_f32_16x16x32_bf16 v[24:27], v[212:215], v[196:199], 0
	v_mfma_f32_16x16x32_bf16 v[16:19], v[220:223], v[196:199], 0
	v_mfma_f32_16x16x32_bf16 v[8:11], v[212:215], v[204:207], 0
	v_mfma_f32_16x16x32_bf16 v[0:3], v[220:223], v[204:207], 0
	v_mfma_f32_16x16x32_bf16 v[56:59], v[216:219], v[168:171], v[56:59]
	v_mfma_f32_16x16x32_bf16 v[48:51], v[224:227], v[168:171], v[48:51]
	v_mfma_f32_16x16x32_bf16 v[40:43], v[216:219], v[192:195], v[40:43]
	v_mfma_f32_16x16x32_bf16 v[32:35], v[224:227], v[192:195], v[32:35]
	v_mfma_f32_16x16x32_bf16 v[24:27], v[216:219], v[200:203], v[24:27]
	v_mfma_f32_16x16x32_bf16 v[16:19], v[224:227], v[200:203], v[16:19]
	v_mfma_f32_16x16x32_bf16 v[8:11], v[216:219], v[208:211], v[8:11]
	v_mfma_f32_16x16x32_bf16 v[0:3], v[224:227], v[208:211], v[0:3]
	s_setprio 0
	s_add_i32 s39, 0, 0x18000
	v_add_u32_e32 v147, s39, v137
	s_barrier
	ds_read_b128 v[140:143], v147
	ds_read_b128 v[152:155], v147 offset:1024
	ds_read_b128 v[156:159], v147 offset:2048
	ds_read_b128 v[160:163], v147 offset:3072
	s_add_u32 s22, s22, 0x40000
	s_addc_u32 s23, s23, 0
	s_mov_b32 m0, s29
	v_lshl_add_u64 v[180:181], s[22:23], 0, v[144:145]
	ds_read_b128 v[164:167], v139 offset:32768
	ds_read_b128 v[168:171], v139 offset:33792
	ds_read_b128 v[188:191], v139 offset:34816
	ds_read_b128 v[192:195], v139 offset:35840
	ds_read_b128 v[196:199], v139 offset:36864
	ds_read_b128 v[200:203], v139 offset:37888
	ds_read_b128 v[204:207], v139 offset:38912
	ds_read_b128 v[208:211], v139 offset:39936
	global_load_lds_dwordx4 v[180:181], off
	v_lshl_add_u64 v[180:181], s[22:23], 0, v[128:129]
	s_mov_b32 m0, s30
	s_nop 0
	global_load_lds_dwordx4 v[180:181], off
	s_waitcnt lgkmcnt(8)
	s_barrier
	s_waitcnt lgkmcnt(0)
	s_setprio 1
	s_waitcnt lgkmcnt(0)
	v_mfma_f32_16x16x32_bf16 v[124:127], v[140:143], v[164:167], v[124:127]
	v_mfma_f32_16x16x32_bf16 v[116:119], v[156:159], v[164:167], v[116:119]
	v_mfma_f32_16x16x32_bf16 v[108:111], v[140:143], v[188:191], v[108:111]
	v_mfma_f32_16x16x32_bf16 v[100:103], v[156:159], v[188:191], v[100:103]
	v_mfma_f32_16x16x32_bf16 v[92:95], v[140:143], v[196:199], v[92:95]
	v_mfma_f32_16x16x32_bf16 v[84:87], v[156:159], v[196:199], v[84:87]
	v_mfma_f32_16x16x32_bf16 v[76:79], v[140:143], v[204:207], v[76:79]
	v_mfma_f32_16x16x32_bf16 v[68:71], v[156:159], v[204:207], v[68:71]
	v_mfma_f32_16x16x32_bf16 v[124:127], v[152:155], v[168:171], v[124:127]
	v_mfma_f32_16x16x32_bf16 v[116:119], v[160:163], v[168:171], v[116:119]
	v_mfma_f32_16x16x32_bf16 v[108:111], v[152:155], v[192:195], v[108:111]
	v_mfma_f32_16x16x32_bf16 v[100:103], v[160:163], v[192:195], v[100:103]
	v_mfma_f32_16x16x32_bf16 v[92:95], v[152:155], v[200:203], v[92:95]
	v_mfma_f32_16x16x32_bf16 v[84:87], v[160:163], v[200:203], v[84:87]
	v_mfma_f32_16x16x32_bf16 v[76:79], v[152:155], v[208:211], v[76:79]
	v_mfma_f32_16x16x32_bf16 v[68:71], v[160:163], v[208:211], v[68:71]
	s_setprio 0
	s_barrier
	s_add_i32 s22, 0, 0x1c000
	s_add_i32 s23, s39, s25
	v_add_u32_e32 v147, s22, v137
	v_lshl_add_u64 v[134:135], v[134:135], 0, s[64:65]
	s_mov_b32 m0, s23
	ds_read_b128 v[212:215], v147
	ds_read_b128 v[216:219], v147 offset:1024
	ds_read_b128 v[220:223], v147 offset:2048
	ds_read_b128 v[224:227], v147 offset:3072
	global_load_lds_dwordx4 v[134:135], off
	v_lshl_add_u64 v[134:135], v[172:173], 0, s[64:65]
	s_add_i32 m0, s23, 0x2000
	s_nop 0
	global_load_lds_dwordx4 v[134:135], off
	s_barrier
; #define PG8_STAGE(bufoff, gbase, voff) do { _Pragma("unroll") for (int _i = 0; _i < 2; ++_i) \
;         __builtin_amdgcn_global_load_lds((const unsigned*)((const char*)(gbase) + (voff)[_i]), (LAS unsigned*)(lds + (bufoff) + ldsw + _i * 8192), 16, 0, 0); } while (0)
; #define PG8_LDA(dst, b, h) do { _Pragma("unroll") for (int m = 0; m < 4; ++m) _Pragma("unroll") for (int k = 0; k < 2; ++k) dst[m][k] = *(const LAS bf16x8*)(lds + PG8_SA(b, h) + aoff + m * 2048 + k * 1024); } while (0)
; #define PG8_LDB(dst, b, h) do { _Pragma("unroll") for (int n = 0; n < 2; ++n) _Pragma("unroll") for (int k = 0; k < 2; ++k) dst[n][k] = *(const LAS bf16x8*)(lds + PG8_SB(b, h) + boff + n * 2048 + k * 1024); } while (0)
; #define PG8_MMA(ai, bj, At, Bt) do { __builtin_amdgcn_s_setprio(1); _Pragma("unroll") for (int m = 0; m < 4; ++m) _Pragma("unroll") for (int n = 0; n < 2; ++n) _Pragma("unroll") for (int k = 0; k < 2; ++k) \
;         acc[ai][bj][m][n] = __builtin_amdgcn_mfma_f32_16x16x32_bf16(Bt[n][k], At[m][k], acc[ai][bj][m][n], 0, 0, 0); __builtin_amdgcn_s_setprio(0); } while (0)
; #define PG8_WAIT_V(n) asm volatile("s_waitcnt vmcnt(" #n ")" ::: "memory")
; #define PG8_WAIT_L(n) asm volatile("s_waitcnt lgkmcnt(" #n ")" ::: "memory")
; #define PG8_BAR __builtin_amdgcn_s_barrier()
; #define PG8_SCHED __builtin_amdgcn_sched_barrier(0)
; template <class Epi, class Sched>
; __device__ __forceinline__ void gemm_phase(LAS unsigned char* lds, const Gemm g, const Sched& S, const Epi& E, const Ids I) {
;     ...
;             PG8_WAIT_L(8); PG8_BAR; PG8_WAIT_L(0); PG8_MMA(0, 0, At, B0); PG8_BAR; PG8_SCHED;
;             PG8_LDB(B1, 1, 1); PG8_STAGE(PG8_SB(1, 0), b3, voffB);
;             PG8_BAR; PG8_WAIT_L(0); PG8_MMA(0, 1, At, B1); PG8_BAR;
;             PG8_LDA(At, 1, 1); PG8_STAGE(PG8_SA(1, 0), a3, voffA);
;             PG8_BAR; PG8_WAIT_L(0); PG8_MMA(1, 0, At, B0); PG8_BAR; PG8_SCHED;
;             PG8_STAGE(PG8_SB(1, 1), b3 + hstep, voffB);
;             PG8_WAIT_V(6); PG8_BAR; PG8_MMA(1, 1, At, B1); PG8_BAR;
	s_waitcnt lgkmcnt(0)
	s_setprio 1
	s_waitcnt lgkmcnt(0)
	v_mfma_f32_16x16x32_bf16 v[120:123], v[212:215], v[164:167], v[120:123]
	v_mfma_f32_16x16x32_bf16 v[112:115], v[220:223], v[164:167], v[112:115]
	v_mfma_f32_16x16x32_bf16 v[104:107], v[212:215], v[188:191], v[104:107]
	v_mfma_f32_16x16x32_bf16 v[96:99], v[220:223], v[188:191], v[96:99]
	v_mfma_f32_16x16x32_bf16 v[88:91], v[212:215], v[196:199], v[88:91]
	v_mfma_f32_16x16x32_bf16 v[80:83], v[220:223], v[196:199], v[80:83]
	v_mfma_f32_16x16x32_bf16 v[72:75], v[212:215], v[204:207], v[72:75]
	v_mfma_f32_16x16x32_bf16 v[64:67], v[220:223], v[204:207], v[64:67]
	v_mfma_f32_16x16x32_bf16 v[120:123], v[216:219], v[168:171], v[120:123]
	v_mfma_f32_16x16x32_bf16 v[112:115], v[224:227], v[168:171], v[112:115]
	v_mfma_f32_16x16x32_bf16 v[104:107], v[216:219], v[192:195], v[104:107]
	v_mfma_f32_16x16x32_bf16 v[96:99], v[224:227], v[192:195], v[96:99]
	v_mfma_f32_16x16x32_bf16 v[88:91], v[216:219], v[200:203], v[88:91]
	v_mfma_f32_16x16x32_bf16 v[80:83], v[224:227], v[200:203], v[80:83]
	v_mfma_f32_16x16x32_bf16 v[72:75], v[216:219], v[208:211], v[72:75]
	v_mfma_f32_16x16x32_bf16 v[64:67], v[224:227], v[208:211], v[64:67]
	s_setprio 0
	s_mov_b32 m0, s31
	v_lshl_add_u64 v[134:135], v[176:177], 0, s[64:65]
	s_barrier
	ds_read_b128 v[164:167], v139 offset:49152
	ds_read_b128 v[168:171], v139 offset:50176
	ds_read_b128 v[188:191], v139 offset:51200
	ds_read_b128 v[192:195], v139 offset:52224
	ds_read_b128 v[196:199], v139 offset:53248
	ds_read_b128 v[200:203], v139 offset:54272
	ds_read_b128 v[204:207], v139 offset:55296
	ds_read_b128 v[208:211], v139 offset:56320
	global_load_lds_dwordx4 v[134:135], off
	v_lshl_add_u64 v[134:135], v[178:179], 0, s[64:65]
	s_mov_b32 m0, s34
	s_nop 0
	global_load_lds_dwordx4 v[134:135], off
	s_barrier
	s_waitcnt lgkmcnt(0)
	s_setprio 1
	s_waitcnt lgkmcnt(0)
	v_mfma_f32_16x16x32_bf16 v[60:63], v[140:143], v[164:167], v[60:63]
	v_mfma_f32_16x16x32_bf16 v[52:55], v[156:159], v[164:167], v[52:55]
	v_mfma_f32_16x16x32_bf16 v[44:47], v[140:143], v[188:191], v[44:47]
	v_mfma_f32_16x16x32_bf16 v[36:39], v[156:159], v[188:191], v[36:39]
	v_mfma_f32_16x16x32_bf16 v[28:31], v[140:143], v[196:199], v[28:31]
	v_mfma_f32_16x16x32_bf16 v[20:23], v[156:159], v[196:199], v[20:23]
	v_mfma_f32_16x16x32_bf16 v[12:15], v[140:143], v[204:207], v[12:15]
	v_mfma_f32_16x16x32_bf16 v[4:7], v[156:159], v[204:207], v[4:7]
	v_mfma_f32_16x16x32_bf16 v[60:63], v[152:155], v[168:171], v[60:63]
	v_mfma_f32_16x16x32_bf16 v[52:55], v[160:163], v[168:171], v[52:55]
	v_mfma_f32_16x16x32_bf16 v[44:47], v[152:155], v[192:195], v[44:47]
	v_mfma_f32_16x16x32_bf16 v[36:39], v[160:163], v[192:195], v[36:39]
	v_mfma_f32_16x16x32_bf16 v[28:31], v[152:155], v[200:203], v[28:31]
	v_mfma_f32_16x16x32_bf16 v[20:23], v[160:163], v[200:203], v[20:23]
	v_mfma_f32_16x16x32_bf16 v[12:15], v[152:155], v[208:211], v[12:15]
	v_mfma_f32_16x16x32_bf16 v[4:7], v[160:163], v[208:211], v[4:7]
	s_setprio 0
	s_barrier
	s_add_u32 s20, s20, 0x40080
	s_addc_u32 s21, s21, 0
	s_add_i32 s22, s22, s25
	v_lshl_add_u64 v[134:135], s[20:21], 0, v[144:145]
	s_mov_b32 m0, s22
	s_nop 0
	global_load_lds_dwordx4 v[134:135], off
	v_lshl_add_u64 v[134:135], s[20:21], 0, v[128:129]
	s_add_i32 m0, s22, 0x2000
	s_nop 0
	global_load_lds_dwordx4 v[134:135], off
	s_waitcnt vmcnt(6)
	s_barrier
	s_setprio 1
	v_mfma_f32_16x16x32_bf16 v[56:59], v[212:215], v[164:167], v[56:59]
	v_mfma_f32_16x16x32_bf16 v[48:51], v[220:223], v[164:167], v[48:51]
	v_mfma_f32_16x16x32_bf16 v[40:43], v[212:215], v[188:191], v[40:43]
	v_mfma_f32_16x16x32_bf16 v[32:35], v[220:223], v[188:191], v[32:35]
	v_mfma_f32_16x16x32_bf16 v[24:27], v[212:215], v[196:199], v[24:27]
	v_mfma_f32_16x16x32_bf16 v[16:19], v[220:223], v[196:199], v[16:19]
	v_mfma_f32_16x16x32_bf16 v[8:11], v[212:215], v[204:207], v[8:11]
	v_mfma_f32_16x16x32_bf16 v[0:3], v[220:223], v[204:207], v[0:3]
	v_mfma_f32_16x16x32_bf16 v[56:59], v[216:219], v[168:171], v[56:59]
	v_mfma_f32_16x16x32_bf16 v[48:51], v[224:227], v[168:171], v[48:51]
	v_mfma_f32_16x16x32_bf16 v[40:43], v[216:219], v[192:195], v[40:43]
	v_mfma_f32_16x16x32_bf16 v[32:35], v[224:227], v[192:195], v[32:35]
	v_mfma_f32_16x16x32_bf16 v[24:27], v[216:219], v[200:203], v[24:27]
	v_mfma_f32_16x16x32_bf16 v[16:19], v[224:227], v[200:203], v[16:19]
	v_mfma_f32_16x16x32_bf16 v[8:11], v[216:219], v[208:211], v[8:11]
	v_mfma_f32_16x16x32_bf16 v[0:3], v[224:227], v[208:211], v[0:3]
	s_setprio 0
	s_add_i32 s38, s38, 2
	s_add_u32 s18, s18, 0x100
	s_addc_u32 s19, s19, 0
	s_add_u32 s36, s36, 0x100
	s_addc_u32 s37, s37, 0
	s_cmp_gt_u32 s38, 13
	s_barrier

; __device__ __forceinline__ void phase_m2(PP P, int l, LAS unsigned char* lds, const Ids I) {
;     ...
;     for (int idx = tid; idx < 5 * 136; idx += 512) { SGH[11 * 136 + idx] = (bf16_t)0; SGL[11 * 136 + idx] = (bf16_t)0; }
;     for (int u = BID; u < MT / 11; u += NB) {
;         const int r0 = u * 11;
; #pragma unroll
;         for (int i = 0; i < 3; ++i) { const int idx = tid + 512 * i; if (idx < 11 * 128) { const int tok = idx >> 7, col = idx & 127, r = r0 + tok, t = t_in_seq(r);
;             const float cur = bf2f(PR[(size_t)r * INW + 2688 + col]);
;             const float prev = t > 0 ? bf2f(PR[(size_t)(r - 1) * INW + 2688 + col]) : (r < MTP ? 0.f : P->in[I_SSHIFT][((size_t)l * 128 + ((r - MTP) >> 2)) * PW + 1664 + col]);
;             const float sg = sigmoidf(cur + (prev - cur) * mu[1664 + col]); const bf16_t h = f2bf(sg);
;             SGH[tok * 136 + col] = h; SGL[tok * 136 + col] = f2bf(sg - bf2f(h)); } }
; #pragma unroll
;         for (int i = 0; i < 2; ++i) { const int idx = tid + 512 * i; if (idx < 11 * 64) { const int tok = idx >> 6, c8 = (idx & 63) * 8; const size_t r = (size_t)r0 + tok; float f[8];
;             unpack8(*(const u32x4*)(ymix + r * 1024 + 512 + c8), f); *(LAS f32x4*)(LY + tok * 512 + c8) = (f32x4){f[0], f[1], f[2], f[3]}; *(LAS f32x4*)(LY + tok * 512 + c8 + 4) = (f32x4){f[4], f[5], f[6], f[7]};
;             unpack8(*(const u32x4*)(arr + A_R * AS + r * 512 + c8), f); *(LAS f32x4*)(LR + tok * 512 + c8) = (f32x4){f[0], f[1], f[2], f[3]}; *(LAS f32x4*)(LR + tok * 512 + c8 + 4) = (f32x4){f[4], f[5], f[6], f[7]};
;             unpack8(*(const u32x4*)(arr + A_KF * AS + r * 512 + c8), f); *(LAS f32x4*)(LK + tok * 512 + c8) = (f32x4){f[0], f[1], f[2], f[3]}; *(LAS f32x4*)(LK + tok * 512 + c8 + 4) = (f32x4){f[4], f[5], f[6], f[7]};
;             unpack8(*(const u32x4*)(arr + A_V * AS + r * 512 + c8), f); *(LAS f32x4*)(LV + tok * 512 + c8) = (f32x4){f[0], f[1], f[2], f[3]}; *(LAS f32x4*)(LV + tok * 512 + c8 + 4) = (f32x4){f[4], f[5], f[6], f[7]}; } }
;         __syncthreads();
;         { f32x4 ag[4];
; #pragma unroll
;           for (int nt = 0; nt < 4; ++nt) ag[nt] = (f32x4){0.f, 0.f, 0.f, 0.f};
; #pragma unroll
;           for (int ks = 0; ks < 4; ++ks) { const bf16x8 fh = *(const LAS bf16x8*)(SGH + l15 * 136 + ks * 32 + quad * 8), fl = *(const LAS bf16x8*)(SGL + l15 * 136 + ks * 32 + quad * 8);
; #pragma unroll
.LBB0_430:
	s_or_b64 exec, exec, s[6:7]
	s_cmpk_gt_i32 s93, 0x5ff
	s_cbranch_scc1 .LBB0_499
	v_readlane_b32 s1, v254, 42
	s_add_u32 s4, s4, s1
	v_and_b32_e32 v154, 0x7f, v128
	s_addc_u32 s5, s5, 0
	s_lshl_b32 s0, s0, 2
	v_lshlrev_b32_e32 v144, 2, v154
	s_add_i32 s3, s0, 0
	v_lshl_add_u64 v[130:131], s[4:5], 0, v[144:145]
	s_mov_b64 s[0:1], 0x1a00
	v_lshlrev_b32_e32 v129, 3, v136
	v_lshl_add_u64 v[156:157], v[130:131], 0, s[0:1]
	v_and_b32_e32 v129, 0x1f8, v129
	v_readlane_b32 s0, v254, 35
	v_lshlrev_b32_e32 v144, 1, v129
	v_readlane_b32 s1, v254, 36
	v_lshlrev_b32_e32 v130, 2, v129
	v_add_u32_e32 v132, 0, v130
	v_lshl_add_u64 v[158:159], s[0:1], 0, v[144:145]
	v_readlane_b32 s0, v254, 37
	v_readlane_b32 s1, v254, 38
	s_add_i32 s3, s3, 0x18200
	v_lshlrev_b32_e32 v131, 1, v139
	v_lshl_add_u64 v[160:161], s[0:1], 0, v[144:145]
	v_readlane_b32 s0, v254, 39
	v_readlane_b32 s1, v254, 40
	v_lshl_add_u32 v134, v138, 2, s3
	v_ashrrev_i32_e32 v188, 7, v128
	v_lshl_add_u64 v[162:163], s[0:1], 0, v[144:145]
	v_readlane_b32 s0, v254, 6
	s_movk_i32 s3, 0x88
	v_add_u32_e32 v135, 0x200, v128
	v_add_u32_e32 v129, s0, v130
	v_mul_u32_u24_e32 v130, 0x88, v138
	v_lshlrev_b32_e32 v130, 1, v130
	s_movk_i32 s0, 0x580
	v_add3_u32 v187, 0, v130, v131
	v_cmp_gt_i32_e64 s[4:5], s0, v128
	v_mad_u64_u32 v[130:131], s[0:1], v188, s3, v[154:155]
	s_movk_i32 s0, 0x380
	v_ashrrev_i32_e32 v190, 7, v135
	v_lshl_add_u32 v189, v130, 1, 0
	v_cmp_gt_i32_e64 s[6:7], s0, v128
	v_mad_u64_u32 v[130:131], s[0:1], v190, s3, v[154:155]
	v_lshl_add_u32 v191, v130, 1, 0
	v_add_u32_e32 v130, 0x400, v128
	s_movk_i32 s0, 0x180
	v_ashrrev_i32_e32 v192, 7, v130
	v_cmp_gt_i32_e64 s[8:9], s0, v128
	v_mad_u64_u32 v[130:131], s[0:1], v192, s3, v[154:155]
	s_movk_i32 s0, 0x2c0
	s_nop 0
	v_cmp_gt_i32_e64 s[10:11], s0, v128
	v_ashrrev_i32_e32 v164, 6, v128
	s_movk_i32 s0, 0xc0
	v_ashrrev_i32_e32 v166, 6, v135
	v_lshlrev_b32_e32 v133, 2, v137
	v_lshl_add_u32 v193, v130, 1, 0
	v_lshlrev_b32_e32 v130, 11, v164
	v_cmp_gt_i32_e64 s[12:13], s0, v128
	v_lshlrev_b32_e32 v128, 11, v166
	v_add_u32_e32 v194, v132, v130
	v_add_u32_e32 v195, v129, v130
	v_add_u32_e32 v197, v129, v128
	v_or_b32_e32 v129, 1, v133
	v_or_b32_e32 v130, 2, v133
	v_or_b32_e32 v131, 3, v133
	s_lshl_b32 s0, s25, 8
	v_add_u32_e32 v196, v132, v128
	v_lshlrev_b32_e32 v128, 13, v137
	v_cmp_gt_u32_e64 s[16:17], 11, v129
	v_lshlrev_b32_e32 v129, 11, v129
	v_cmp_gt_u32_e64 s[18:19], 11, v130
	v_lshlrev_b32_e32 v130, 11, v130
	v_cmp_gt_u32_e64 s[20:21], 11, v131
	v_lshlrev_b32_e32 v131, 11, v131
	s_add_i32 s0, s0, 0
	v_ashrrev_i32_e32 v165, 31, v164
	v_ashrrev_i32_e32 v167, 31, v166
	v_cmp_ne_u32_e64 s[14:15], 3, v137
	v_lshl_add_u64 v[168:169], s[78:79], 0, v[144:145]
	v_lshl_add_u32 v198, v136, 2, s0
	v_add_u32_e32 v199, v134, v128
	v_add_u32_e32 v200, v134, v129
	v_add_u32_e32 v201, v134, v130
	v_add_u32_e32 v202, v134, v131
	s_mov_b32 s3, s93
	s_branch .LBB0_433
	s_nop 0
	s_nop 0
	s_nop 0
	s_nop 0
	s_nop 0
	s_nop 0
	s_nop 0
	s_nop 0
	s_nop 0
	s_nop 0
	s_nop 0
	s_nop 0
	s_nop 0
	s_nop 0
	s_nop 0
	s_nop 0
	s_nop 0
	s_nop 0
	s_nop 0
	s_nop 0
.LBB0_432:
	s_or_b64 exec, exec, s[0:1]
	s_add_i32 s3, s3, s72
	s_cmpk_gt_i32 s3, 0x5ff
	s_barrier
	s_cbranch_scc1 .LBB0_499
